# gsu epilogue: the eight u loads issued together with counted waits
# speedup vs baseline: 1.0078x; 1.0078x over previous
.LBB0_915:
	v_add_u32_e32 v0, v117, v110
	v_mov_b64_e32 v[2:3], s[12:13]
	v_mad_i64_i32 v[4:5], s[6:7], v0, s19, v[2:3]
	v_ashrrev_i32_e32 v1, 31, v0
	v_readlane_b32 s6, v255, 35
	v_lshlrev_b64 v[0:1], 11, v[0:1]
	v_readlane_b32 s7, v255, 36
	v_lshl_or_b32 v48, v124, 8, v122
	v_add_u32_e32 v177, s73, v177
	v_lshl_add_u64 v[2:3], s[6:7], 0, v[0:1]
	v_lshl_add_u64 v[0:1], v[4:5], 0, v[48:49]
	global_load_dwordx2 v[156:157], v[0:1], off
	global_load_dwordx2 v[158:159], v[0:1], off offset:32
	global_load_dwordx2 v[160:161], v[0:1], off offset:64
	global_load_dwordx2 v[162:163], v[0:1], off offset:96
	global_load_dwordx2 v[164:165], v[0:1], off offset:128
	global_load_dwordx2 v[166:167], v[0:1], off offset:160
	global_load_dwordx2 v[168:169], v[0:1], off offset:192
	global_load_dwordx2 v[170:171], v[0:1], off offset:224
	v_lshl_add_u64 v[2:3], v[2:3], 0, v[48:49]
	s_mov_b64 s[6:7], 0x60
	v_cmp_lt_i32_e32 vcc, 63, v177
	s_or_b64 s[44:45], vcc, s[44:45]
	s_waitcnt vmcnt(7)
	v_lshlrev_b32_e32 v4, 16, v156
	v_and_b32_e32 v5, 0xffff0000, v156
	v_mul_f32_e32 v6, 0x3d372713, v4
	v_mul_f32_e32 v6, v6, v4
	v_mov_b32_e32 v8, v4
	v_fmac_f32_e32 v8, v6, v8
	v_mul_f32_e32 v6, 0xbfcc422a, v8
	v_mul_f32_e32 v6, 0x3fb8aa3b, v6
	v_exp_f32_e32 v6, v6
	v_mov_b32_e32 v9, v5
	v_add_f32_e32 v6, 1.0, v6
	v_rcp_f32_e32 v8, v6
	v_mul_f32_e32 v6, 0x3d372713, v5
	v_mul_f32_e32 v6, v6, v5
	v_fmac_f32_e32 v9, v6, v9
	v_mul_f32_e32 v6, 0xbfcc422a, v9
	v_mul_f32_e32 v6, 0x3fb8aa3b, v6
	v_exp_f32_e32 v6, v6
	s_nop 0
	v_add_f32_e32 v6, 1.0, v6
	v_rcp_f32_e32 v9, v6
	v_lshlrev_b32_e32 v6, 16, v157
	v_and_b32_e32 v7, 0xffff0000, v157
	v_mov_b32_e32 v10, v7
	v_pk_mul_f32 v[4:5], v[8:9], v[4:5]
	v_pk_add_f32 v[8:9], v[118:119], v[44:45] op_sel_hi:[0,1]
	v_pk_mul_f32 v[4:5], v[8:9], v[4:5]
	v_mul_f32_e32 v8, 0x3d372713, v6
	v_mul_f32_e32 v8, v8, v6
	v_mov_b32_e32 v9, v6
	v_fmac_f32_e32 v9, v8, v9
	v_mul_f32_e32 v8, 0xbfcc422a, v9
	v_mul_f32_e32 v9, 0x3d372713, v7
	v_mul_f32_e32 v9, v9, v7
	v_fmac_f32_e32 v10, v9, v10
	v_mul_f32_e32 v9, 0xbfcc422a, v10
	v_mul_f32_e32 v8, 0x3fb8aa3b, v8
	v_mul_f32_e32 v9, 0x3fb8aa3b, v9
	v_exp_f32_e32 v8, v8
	v_exp_f32_e32 v9, v9
	v_cvt_pk_bf16_f32 v4, v4, v5
	v_add_f32_e32 v8, 1.0, v8
	v_add_f32_e32 v9, 1.0, v9
	v_rcp_f32_e32 v8, v8
	v_rcp_f32_e32 v9, v9
	s_nop 0
	v_pk_mul_f32 v[6:7], v[8:9], v[6:7]
	v_pk_add_f32 v[8:9], v[118:119], v[46:47] op_sel_hi:[0,1]
	v_pk_mul_f32 v[6:7], v[8:9], v[6:7]
	s_nop 0
	v_cvt_pk_bf16_f32 v5, v6, v7
	global_store_dwordx2 v[2:3], v[4:5], off
	s_waitcnt vmcnt(7)
	v_lshlrev_b32_e32 v6, 16, v158
	v_and_b32_e32 v7, 0xffff0000, v158
	v_mul_f32_e32 v4, 0x3d372713, v6
	v_mul_f32_e32 v4, v4, v6
	v_mov_b32_e32 v8, v6
	v_fmac_f32_e32 v8, v4, v8
	v_mul_f32_e32 v4, 0xbfcc422a, v8
	v_mul_f32_e32 v4, 0x3fb8aa3b, v4
	v_exp_f32_e32 v4, v4
	v_mov_b32_e32 v9, v7
	v_add_f32_e32 v4, 1.0, v4
	v_rcp_f32_e32 v8, v4
	v_mul_f32_e32 v4, 0x3d372713, v7
	v_mul_f32_e32 v4, v4, v7
	v_fmac_f32_e32 v9, v4, v9
	v_mul_f32_e32 v4, 0xbfcc422a, v9
	v_mul_f32_e32 v4, 0x3fb8aa3b, v4
	v_exp_f32_e32 v4, v4
	s_nop 0
	v_add_f32_e32 v4, 1.0, v4
	v_rcp_f32_e32 v9, v4
	v_lshlrev_b32_e32 v4, 16, v159
	v_and_b32_e32 v5, 0xffff0000, v159
	v_mov_b32_e32 v10, v5
	v_pk_mul_f32 v[6:7], v[8:9], v[6:7]
	v_pk_add_f32 v[8:9], v[118:119], v[40:41] op_sel_hi:[0,1]
	v_pk_mul_f32 v[6:7], v[8:9], v[6:7]
	v_mul_f32_e32 v8, 0x3d372713, v4
	v_mul_f32_e32 v8, v8, v4
	v_mov_b32_e32 v9, v4
	v_fmac_f32_e32 v9, v8, v9
	v_mul_f32_e32 v8, 0xbfcc422a, v9
	v_mul_f32_e32 v9, 0x3d372713, v5
	v_mul_f32_e32 v9, v9, v5
	v_fmac_f32_e32 v10, v9, v10
	v_mul_f32_e32 v9, 0xbfcc422a, v10
	v_mul_f32_e32 v8, 0x3fb8aa3b, v8
	v_mul_f32_e32 v9, 0x3fb8aa3b, v9
	v_exp_f32_e32 v8, v8
	v_exp_f32_e32 v9, v9
	v_cvt_pk_bf16_f32 v6, v6, v7
	v_add_f32_e32 v8, 1.0, v8
	v_add_f32_e32 v9, 1.0, v9
	v_rcp_f32_e32 v8, v8
	v_rcp_f32_e32 v9, v9
	s_nop 0
	v_pk_mul_f32 v[4:5], v[8:9], v[4:5]
	v_pk_add_f32 v[8:9], v[118:119], v[42:43] op_sel_hi:[0,1]
	v_pk_mul_f32 v[4:5], v[8:9], v[4:5]
	v_lshl_add_u64 v[8:9], v[2:3], 0, 32
	v_cvt_pk_bf16_f32 v7, v4, v5
	global_store_dwordx2 v[8:9], v[6:7], off
	s_waitcnt vmcnt(7)
	v_lshlrev_b32_e32 v6, 16, v160
	v_and_b32_e32 v7, 0xffff0000, v160
	v_mul_f32_e32 v4, 0x3d372713, v6
	v_mul_f32_e32 v4, v4, v6
	v_mov_b32_e32 v8, v6
	v_fmac_f32_e32 v8, v4, v8
	v_mul_f32_e32 v4, 0xbfcc422a, v8
	v_mul_f32_e32 v4, 0x3fb8aa3b, v4
	v_exp_f32_e32 v4, v4
	v_mov_b32_e32 v9, v7
	v_add_f32_e32 v4, 1.0, v4
	v_rcp_f32_e32 v8, v4
	v_mul_f32_e32 v4, 0x3d372713, v7
	v_mul_f32_e32 v4, v4, v7
	v_fmac_f32_e32 v9, v4, v9
	v_mul_f32_e32 v4, 0xbfcc422a, v9
	v_mul_f32_e32 v4, 0x3fb8aa3b, v4
	v_exp_f32_e32 v4, v4
	s_nop 0
	v_add_f32_e32 v4, 1.0, v4
	v_rcp_f32_e32 v9, v4
	v_lshlrev_b32_e32 v4, 16, v161
	v_and_b32_e32 v5, 0xffff0000, v161
	v_mov_b32_e32 v10, v5
	v_pk_mul_f32 v[6:7], v[8:9], v[6:7]
	v_pk_add_f32 v[8:9], v[118:119], v[36:37] op_sel_hi:[0,1]
	v_pk_mul_f32 v[6:7], v[8:9], v[6:7]
	v_mul_f32_e32 v8, 0x3d372713, v4
	v_mul_f32_e32 v8, v8, v4
	v_mov_b32_e32 v9, v4
	v_fmac_f32_e32 v9, v8, v9
	v_mul_f32_e32 v8, 0xbfcc422a, v9
	v_mul_f32_e32 v9, 0x3d372713, v5
	v_mul_f32_e32 v9, v9, v5
	v_fmac_f32_e32 v10, v9, v10
	v_mul_f32_e32 v9, 0xbfcc422a, v10
	v_mul_f32_e32 v8, 0x3fb8aa3b, v8
	v_mul_f32_e32 v9, 0x3fb8aa3b, v9
	v_exp_f32_e32 v8, v8
	v_exp_f32_e32 v9, v9
	v_cvt_pk_bf16_f32 v6, v6, v7
	v_add_f32_e32 v8, 1.0, v8
	v_add_f32_e32 v9, 1.0, v9
	v_rcp_f32_e32 v8, v8
	v_rcp_f32_e32 v9, v9
	s_nop 0
	v_pk_mul_f32 v[4:5], v[8:9], v[4:5]
	v_pk_add_f32 v[8:9], v[118:119], v[38:39] op_sel_hi:[0,1]
	v_pk_mul_f32 v[4:5], v[8:9], v[4:5]
	v_lshl_add_u64 v[8:9], v[2:3], 0, 64
	v_cvt_pk_bf16_f32 v7, v4, v5
	global_store_dwordx2 v[8:9], v[6:7], off
	s_waitcnt vmcnt(7)
	v_lshlrev_b32_e32 v6, 16, v162
	v_and_b32_e32 v7, 0xffff0000, v162
	v_mul_f32_e32 v4, 0x3d372713, v6
	v_mul_f32_e32 v4, v4, v6
	v_mov_b32_e32 v8, v6
	v_fmac_f32_e32 v8, v4, v8
	v_mul_f32_e32 v4, 0xbfcc422a, v8
	v_mul_f32_e32 v4, 0x3fb8aa3b, v4
	v_exp_f32_e32 v4, v4
	v_mov_b32_e32 v9, v7
	v_add_f32_e32 v4, 1.0, v4
	v_rcp_f32_e32 v8, v4
	v_mul_f32_e32 v4, 0x3d372713, v7
	v_mul_f32_e32 v4, v4, v7
	v_fmac_f32_e32 v9, v4, v9
	v_mul_f32_e32 v4, 0xbfcc422a, v9
	v_mul_f32_e32 v4, 0x3fb8aa3b, v4
	v_exp_f32_e32 v4, v4
	s_nop 0
	v_add_f32_e32 v4, 1.0, v4
	v_rcp_f32_e32 v9, v4
	v_lshlrev_b32_e32 v4, 16, v163
	v_and_b32_e32 v5, 0xffff0000, v163
	v_mov_b32_e32 v10, v5
	v_pk_mul_f32 v[6:7], v[8:9], v[6:7]
	v_pk_add_f32 v[8:9], v[118:119], v[32:33] op_sel_hi:[0,1]
	v_pk_mul_f32 v[6:7], v[8:9], v[6:7]
	v_mul_f32_e32 v8, 0x3d372713, v4
	v_mul_f32_e32 v8, v8, v4
	v_mov_b32_e32 v9, v4
	v_fmac_f32_e32 v9, v8, v9
	v_mul_f32_e32 v8, 0xbfcc422a, v9
	v_mul_f32_e32 v9, 0x3d372713, v5
	v_mul_f32_e32 v9, v9, v5
	v_fmac_f32_e32 v10, v9, v10
	v_mul_f32_e32 v9, 0xbfcc422a, v10
	v_mul_f32_e32 v8, 0x3fb8aa3b, v8
	v_mul_f32_e32 v9, 0x3fb8aa3b, v9
	v_exp_f32_e32 v8, v8
	v_exp_f32_e32 v9, v9
	v_cvt_pk_bf16_f32 v6, v6, v7
	v_add_f32_e32 v8, 1.0, v8
	v_add_f32_e32 v9, 1.0, v9
	v_rcp_f32_e32 v8, v8
	v_rcp_f32_e32 v9, v9
	s_nop 0
	v_pk_mul_f32 v[4:5], v[8:9], v[4:5]
	v_pk_add_f32 v[8:9], v[118:119], v[34:35] op_sel_hi:[0,1]
	v_pk_mul_f32 v[4:5], v[8:9], v[4:5]
	v_lshl_add_u64 v[8:9], v[2:3], 0, s[6:7]
	v_cvt_pk_bf16_f32 v7, v4, v5
	global_store_dwordx2 v[8:9], v[6:7], off
	s_mov_b64 s[6:7], 0xa0
	s_waitcnt vmcnt(7)
	v_lshlrev_b32_e32 v6, 16, v164
	v_and_b32_e32 v7, 0xffff0000, v164
	v_mul_f32_e32 v4, 0x3d372713, v6
	v_mul_f32_e32 v4, v4, v6
	v_mov_b32_e32 v8, v6
	v_fmac_f32_e32 v8, v4, v8
	v_mul_f32_e32 v4, 0xbfcc422a, v8
	v_mul_f32_e32 v4, 0x3fb8aa3b, v4
	v_exp_f32_e32 v4, v4
	v_mov_b32_e32 v9, v7
	v_add_f32_e32 v4, 1.0, v4
	v_rcp_f32_e32 v8, v4
	v_mul_f32_e32 v4, 0x3d372713, v7
	v_mul_f32_e32 v4, v4, v7
	v_fmac_f32_e32 v9, v4, v9
	v_mul_f32_e32 v4, 0xbfcc422a, v9
	v_mul_f32_e32 v4, 0x3fb8aa3b, v4
	v_exp_f32_e32 v4, v4
	s_nop 0
	v_add_f32_e32 v4, 1.0, v4
	v_rcp_f32_e32 v9, v4
	v_lshlrev_b32_e32 v4, 16, v165
	v_and_b32_e32 v5, 0xffff0000, v165
	v_mov_b32_e32 v10, v5
	v_pk_mul_f32 v[6:7], v[8:9], v[6:7]
	v_pk_add_f32 v[8:9], v[118:119], v[28:29] op_sel_hi:[0,1]
	v_pk_mul_f32 v[6:7], v[8:9], v[6:7]
	v_mul_f32_e32 v8, 0x3d372713, v4
	v_mul_f32_e32 v8, v8, v4
	v_mov_b32_e32 v9, v4
	v_fmac_f32_e32 v9, v8, v9
	v_mul_f32_e32 v8, 0xbfcc422a, v9
	v_mul_f32_e32 v9, 0x3d372713, v5
	v_mul_f32_e32 v9, v9, v5
	v_fmac_f32_e32 v10, v9, v10
	v_mul_f32_e32 v9, 0xbfcc422a, v10
	v_mul_f32_e32 v8, 0x3fb8aa3b, v8
	v_mul_f32_e32 v9, 0x3fb8aa3b, v9
	v_exp_f32_e32 v8, v8
	v_exp_f32_e32 v9, v9
	v_cvt_pk_bf16_f32 v6, v6, v7
	v_add_f32_e32 v8, 1.0, v8
	v_add_f32_e32 v9, 1.0, v9
	v_rcp_f32_e32 v8, v8
	v_rcp_f32_e32 v9, v9
	s_nop 0
	v_pk_mul_f32 v[4:5], v[8:9], v[4:5]
	v_pk_add_f32 v[8:9], v[118:119], v[30:31] op_sel_hi:[0,1]
	v_pk_mul_f32 v[4:5], v[8:9], v[4:5]
	v_lshl_add_u64 v[8:9], v[2:3], 0, s[30:31]
	v_cvt_pk_bf16_f32 v7, v4, v5
	global_store_dwordx2 v[8:9], v[6:7], off
	s_waitcnt vmcnt(7)
	v_lshlrev_b32_e32 v6, 16, v166
	v_and_b32_e32 v7, 0xffff0000, v166
	v_mul_f32_e32 v4, 0x3d372713, v6
	v_mul_f32_e32 v4, v4, v6
	v_mov_b32_e32 v8, v6
	v_fmac_f32_e32 v8, v4, v8
	v_mul_f32_e32 v4, 0xbfcc422a, v8
	v_mul_f32_e32 v4, 0x3fb8aa3b, v4
	v_exp_f32_e32 v4, v4
	v_mov_b32_e32 v9, v7
	v_add_f32_e32 v4, 1.0, v4
	v_rcp_f32_e32 v8, v4
	v_mul_f32_e32 v4, 0x3d372713, v7
	v_mul_f32_e32 v4, v4, v7
	v_fmac_f32_e32 v9, v4, v9
	v_mul_f32_e32 v4, 0xbfcc422a, v9
	v_mul_f32_e32 v4, 0x3fb8aa3b, v4
	v_exp_f32_e32 v4, v4
	s_nop 0
	v_add_f32_e32 v4, 1.0, v4
	v_rcp_f32_e32 v9, v4
	v_lshlrev_b32_e32 v4, 16, v167
	v_and_b32_e32 v5, 0xffff0000, v167
	v_mov_b32_e32 v10, v5
	v_pk_mul_f32 v[6:7], v[8:9], v[6:7]
	v_pk_add_f32 v[8:9], v[118:119], v[24:25] op_sel_hi:[0,1]
	v_pk_mul_f32 v[6:7], v[8:9], v[6:7]
	v_mul_f32_e32 v8, 0x3d372713, v4
	v_mul_f32_e32 v8, v8, v4
	v_mov_b32_e32 v9, v4
	v_fmac_f32_e32 v9, v8, v9
	v_mul_f32_e32 v8, 0xbfcc422a, v9
	v_mul_f32_e32 v9, 0x3d372713, v5
	v_mul_f32_e32 v9, v9, v5
	v_fmac_f32_e32 v10, v9, v10
	v_mul_f32_e32 v9, 0xbfcc422a, v10
	v_mul_f32_e32 v8, 0x3fb8aa3b, v8
	v_mul_f32_e32 v9, 0x3fb8aa3b, v9
	v_exp_f32_e32 v8, v8
	v_exp_f32_e32 v9, v9
	v_cvt_pk_bf16_f32 v6, v6, v7
	v_add_f32_e32 v8, 1.0, v8
	v_add_f32_e32 v9, 1.0, v9
	v_rcp_f32_e32 v8, v8
	v_rcp_f32_e32 v9, v9
	s_nop 0
	v_pk_mul_f32 v[4:5], v[8:9], v[4:5]
	v_pk_add_f32 v[8:9], v[118:119], v[26:27] op_sel_hi:[0,1]
	v_pk_mul_f32 v[4:5], v[8:9], v[4:5]
	v_lshl_add_u64 v[8:9], v[2:3], 0, s[6:7]
	v_cvt_pk_bf16_f32 v7, v4, v5
	global_store_dwordx2 v[8:9], v[6:7], off
	s_mov_b64 s[6:7], 0xc0
	s_waitcnt vmcnt(7)
	v_lshlrev_b32_e32 v6, 16, v168
	v_and_b32_e32 v7, 0xffff0000, v168
	v_mul_f32_e32 v4, 0x3d372713, v6
	v_mul_f32_e32 v4, v4, v6
	v_mov_b32_e32 v8, v6
	v_fmac_f32_e32 v8, v4, v8
	v_mul_f32_e32 v4, 0xbfcc422a, v8
	v_mul_f32_e32 v4, 0x3fb8aa3b, v4
	v_exp_f32_e32 v4, v4
	v_mov_b32_e32 v9, v7
	v_add_f32_e32 v4, 1.0, v4
	v_rcp_f32_e32 v8, v4
	v_mul_f32_e32 v4, 0x3d372713, v7
	v_mul_f32_e32 v4, v4, v7
	v_fmac_f32_e32 v9, v4, v9
	v_mul_f32_e32 v4, 0xbfcc422a, v9
	v_mul_f32_e32 v4, 0x3fb8aa3b, v4
	v_exp_f32_e32 v4, v4
	s_nop 0
	v_add_f32_e32 v4, 1.0, v4
	v_rcp_f32_e32 v9, v4
	v_lshlrev_b32_e32 v4, 16, v169
	v_and_b32_e32 v5, 0xffff0000, v169
	v_mov_b32_e32 v10, v5
	v_pk_mul_f32 v[6:7], v[8:9], v[6:7]
	v_pk_add_f32 v[8:9], v[118:119], v[20:21] op_sel_hi:[0,1]
	v_pk_mul_f32 v[6:7], v[8:9], v[6:7]
	v_mul_f32_e32 v8, 0x3d372713, v4
	v_mul_f32_e32 v8, v8, v4
	v_mov_b32_e32 v9, v4
	v_fmac_f32_e32 v9, v8, v9
	v_mul_f32_e32 v8, 0xbfcc422a, v9
	v_mul_f32_e32 v9, 0x3d372713, v5
	v_mul_f32_e32 v9, v9, v5
	v_fmac_f32_e32 v10, v9, v10
	v_mul_f32_e32 v9, 0xbfcc422a, v10
	v_mul_f32_e32 v8, 0x3fb8aa3b, v8
	v_mul_f32_e32 v9, 0x3fb8aa3b, v9
	v_exp_f32_e32 v8, v8
	v_exp_f32_e32 v9, v9
	v_cvt_pk_bf16_f32 v6, v6, v7
	v_add_f32_e32 v8, 1.0, v8
	v_add_f32_e32 v9, 1.0, v9
	v_rcp_f32_e32 v8, v8
	v_rcp_f32_e32 v9, v9
	s_nop 0
	v_pk_mul_f32 v[4:5], v[8:9], v[4:5]
	v_pk_add_f32 v[8:9], v[118:119], v[22:23] op_sel_hi:[0,1]
	v_pk_mul_f32 v[4:5], v[8:9], v[4:5]
	v_lshl_add_u64 v[8:9], v[2:3], 0, s[6:7]
	v_cvt_pk_bf16_f32 v7, v4, v5
	global_store_dwordx2 v[8:9], v[6:7], off
	s_mov_b64 s[6:7], 0xe0
	v_lshl_add_u64 v[2:3], v[2:3], 0, s[6:7]
	v_readlane_b32 s6, v255, 5
	s_waitcnt vmcnt(7)
	v_lshlrev_b32_e32 v4, 16, v170
	v_and_b32_e32 v5, 0xffff0000, v170
	v_mul_f32_e32 v0, 0x3d372713, v4
	v_mul_f32_e32 v0, v0, v4
	v_mov_b32_e32 v6, v4
	v_fmac_f32_e32 v6, v0, v6
	v_mul_f32_e32 v0, 0xbfcc422a, v6
	v_mul_f32_e32 v0, 0x3fb8aa3b, v0
	v_exp_f32_e32 v0, v0
	v_mov_b32_e32 v7, v5
	v_add_u32_e32 v216, s6, v216
	v_add_f32_e32 v0, 1.0, v0
	v_rcp_f32_e32 v6, v0
	v_mul_f32_e32 v0, 0x3d372713, v5
	v_mul_f32_e32 v0, v0, v5
	v_fmac_f32_e32 v7, v0, v7
	v_mul_f32_e32 v0, 0xbfcc422a, v7
	v_mul_f32_e32 v0, 0x3fb8aa3b, v0
	v_exp_f32_e32 v0, v0
	s_nop 0
	v_add_f32_e32 v0, 1.0, v0
	v_rcp_f32_e32 v7, v0
	v_lshlrev_b32_e32 v0, 16, v171
	v_and_b32_e32 v1, 0xffff0000, v171
	v_mov_b32_e32 v8, v1
	v_pk_mul_f32 v[4:5], v[6:7], v[4:5]
	v_pk_add_f32 v[6:7], v[118:119], v[16:17] op_sel_hi:[0,1]
	v_pk_mul_f32 v[4:5], v[6:7], v[4:5]
	v_mul_f32_e32 v6, 0x3d372713, v0
	v_mul_f32_e32 v6, v6, v0
	v_mov_b32_e32 v7, v0
	v_fmac_f32_e32 v7, v6, v7
	v_mul_f32_e32 v6, 0xbfcc422a, v7
	v_mul_f32_e32 v7, 0x3d372713, v1
	v_mul_f32_e32 v7, v7, v1
	v_fmac_f32_e32 v8, v7, v8
	v_mul_f32_e32 v7, 0xbfcc422a, v8
	v_mul_f32_e32 v6, 0x3fb8aa3b, v6
	v_mul_f32_e32 v7, 0x3fb8aa3b, v7
	v_exp_f32_e32 v6, v6
	v_exp_f32_e32 v7, v7
	v_cvt_pk_bf16_f32 v4, v4, v5
	v_add_f32_e32 v6, 1.0, v6
	v_add_f32_e32 v7, 1.0, v7
	v_rcp_f32_e32 v6, v6
	v_rcp_f32_e32 v7, v7
	s_nop 0
	v_pk_mul_f32 v[0:1], v[6:7], v[0:1]
	v_pk_add_f32 v[6:7], v[118:119], v[18:19] op_sel_hi:[0,1]
	v_pk_mul_f32 v[0:1], v[6:7], v[0:1]
	s_nop 0
	v_cvt_pk_bf16_f32 v5, v0, v1
	global_store_dwordx2 v[2:3], v[4:5], off
	s_barrier
	s_andn2_b64 exec, exec, s[44:45]
	s_cbranch_execz .LBB0_952
